# v095 + remaining UP-phase filler conversion stores write-through (sc1)
# baseline (speedup 1.0000x reference)
.LBB0_1399:
	s_andn2_b64 vcc, exec, s[0:1]
	s_cbranch_vccnz .LBB0_1401
	v_readlane_b32 s15, v254, 19
	s_add_i32 s0, s11, 0xf948
	s_and_b32 s1, s0, 0xffff
	v_mov_b32_e32 v2, s15
	ds_read_b64 v[2:3], v2
	s_mul_i32 s1, s1, 0xba2f
	s_lshr_b32 s1, s1, 23
	s_mul_i32 s14, s1, 0xb0
	s_sub_i32 s0, s0, s14
	s_and_b32 s14, s0, 0xffff
	s_waitcnt lgkmcnt(0)
	v_readfirstlane_b32 s15, v2
	s_mul_i32 s18, s36, 0x1600000
	v_readfirstlane_b32 s16, v3
	s_mul_hi_i32 s17, s36, 0x1600000
	s_add_u32 s15, s15, s18
	s_addc_u32 s16, s16, s17
	s_bfe_i32 s0, s0, 0x10002
	s_lshl_b32 s17, s14, 4
	s_and_b32 s0, s0, 0xb00
	s_and_b32 s17, s17, 0xf80
	s_add_i32 s17, s0, s17
	s_lshl_b32 s0, s14, 5
	s_and_b32 s14, s0, 0x60
	s_or_b32 s14, s17, s14
	v_readlane_b32 s17, v252, 9
	s_add_u32 s13, s17, s13
	v_readlane_b32 s17, v252, 10
	s_addc_u32 s12, s17, s12
	s_lshl_b32 s14, s14, 2
	s_add_u32 s14, s15, s14
	v_lshl_or_b32 v4, s1, 6, v35
	s_addc_u32 s15, s16, 0
	v_lshlrev_b32_e32 v98, 2, v34
	v_lshl_add_u64 v[2:3], s[14:15], 0, v[98:99]
	v_mul_u32_u24_e32 v98, 0x5800, v4
	v_lshl_add_u64 v[30:31], v[2:3], 0, v[98:99]
	s_mov_b32 s14, 0x2c000
	v_add_co_u32_e32 v6, vcc, s14, v30
	global_load_dwordx4 v[2:5], v[30:31], off nt
	s_nop 0
	v_addc_co_u32_e32 v7, vcc, 0, v31, vcc
	s_mov_b32 s14, 0x58000
	global_load_dwordx4 v[6:9], v[6:7], off nt
	v_add_co_u32_e32 v10, vcc, s14, v30
	s_mov_b32 s14, 0x84000
	s_nop 0
	v_addc_co_u32_e32 v11, vcc, 0, v31, vcc
	global_load_dwordx4 v[10:13], v[10:11], off nt
	v_add_co_u32_e32 v14, vcc, s14, v30
	s_mov_b32 s14, 0xb0000
	s_nop 0
	v_addc_co_u32_e32 v15, vcc, 0, v31, vcc
	global_load_dwordx4 v[14:17], v[14:15], off nt
	v_add_co_u32_e32 v18, vcc, s14, v30
	s_mov_b32 s14, 0xdc000
	s_nop 0
	v_addc_co_u32_e32 v19, vcc, 0, v31, vcc
	global_load_dwordx4 v[18:21], v[18:19], off nt
	v_add_co_u32_e32 v22, vcc, s14, v30
	s_mov_b32 s14, 0x108000
	s_nop 0
	v_addc_co_u32_e32 v23, vcc, 0, v31, vcc
	global_load_dwordx4 v[22:25], v[22:23], off nt
	v_add_co_u32_e32 v26, vcc, s14, v30
	s_mov_b32 s14, 0x134000
	s_nop 0
	v_addc_co_u32_e32 v27, vcc, 0, v31, vcc
	global_load_dwordx4 v[26:29], v[26:27], off nt
	v_add_co_u32_e32 v30, vcc, s14, v30
	v_add_u32_e32 v41, v37, v45
	s_nop 0
	v_addc_co_u32_e32 v31, vcc, 0, v31, vcc
	global_load_dwordx4 v[30:33], v[30:31], off nt
	s_lshl_b32 s1, s1, 7
	s_add_u32 s14, s13, s1
	s_addc_u32 s15, s12, 0
	v_lshlrev_b32_e32 v98, 1, v36
	s_waitcnt vmcnt(0)
	ds_write2_b32 v41, v2, v3 offset1:1
	ds_write2_b32 v41, v4, v5 offset0:2 offset1:3
	v_add_u32_e32 v2, 0x420, v41
	ds_write2_b32 v2, v6, v7 offset1:1
	v_add_u32_e32 v2, 0x428, v41
	ds_write2_b32 v2, v8, v9 offset1:1
	v_add_u32_e32 v2, 0x840, v41
	v_lshl_add_u64 v[6:7], s[14:15], 0, v[98:99]
	ds_write2_b32 v2, v10, v11 offset1:1
	v_add_u32_e32 v2, 0x848, v41
	ds_write2_b32 v2, v12, v13 offset1:1
	v_add_u32_e32 v2, 0xc60, v41
	ds_write2_b32 v2, v14, v15 offset1:1
	v_add_u32_e32 v2, 0xc68, v41
	ds_write2_b32 v2, v16, v17 offset1:1
	v_add_u32_e32 v2, 0x1080, v41
	ds_write2_b32 v2, v18, v19 offset1:1
	v_add_u32_e32 v2, 0x1088, v41
	ds_write2_b32 v2, v20, v21 offset1:1
	v_add_u32_e32 v2, 0x14a0, v41
	ds_write2_b32 v2, v22, v23 offset1:1
	v_add_u32_e32 v2, 0x14a8, v41
	ds_write2_b32 v2, v24, v25 offset1:1
	v_add_u32_e32 v2, 0x18c0, v41
	ds_write2_b32 v2, v26, v27 offset1:1
	v_add_u32_e32 v2, 0x18c8, v41
	ds_write2_b32 v2, v28, v29 offset1:1
	v_add_u32_e32 v2, 0x1ce0, v41
	ds_write2_b32 v2, v30, v31 offset1:1
	v_add_u32_e32 v2, 0x1ce8, v41
	ds_write2_b32 v2, v32, v33 offset1:1
	s_waitcnt lgkmcnt(0)
	ds_read2_b32 v[8:9], v50 offset0:33 offset1:41
	ds_read2_b32 v[10:11], v50 offset1:8
	ds_read2_b32 v[12:13], v50 offset0:66 offset1:74
	ds_read2_b32 v[14:15], v50 offset0:99 offset1:107
	ds_read2_b32 v[16:17], v50 offset0:132 offset1:140
	ds_read2_b32 v[18:19], v50 offset0:165 offset1:173
	ds_read2_b32 v[20:21], v50 offset0:198 offset1:206
	ds_read2_b32 v[22:23], v50 offset0:231 offset1:239
	s_waitcnt lgkmcnt(6)
	v_cvt_pk_bf16_f32 v2, v10, v8
	v_or_b32_e32 v8, s0, v35
	v_lshlrev_b32_e32 v98, 11, v8
	v_or_b32_e32 v8, s0, v47
	s_waitcnt lgkmcnt(4)
	v_cvt_pk_bf16_f32 v3, v12, v14
	s_waitcnt lgkmcnt(2)
	v_cvt_pk_bf16_f32 v4, v16, v18
	s_waitcnt lgkmcnt(0)
	v_cvt_pk_bf16_f32 v5, v20, v22
	v_lshl_add_u64 v[24:25], v[6:7], 0, v[98:99]
	v_lshlrev_b32_e32 v98, 11, v8
	global_store_dwordx4 v[24:25], v[2:5], off sc1
	s_nop 1
	v_cvt_pk_bf16_f32 v2, v11, v9
	v_cvt_pk_bf16_f32 v3, v13, v15
	v_cvt_pk_bf16_f32 v4, v17, v19
	v_cvt_pk_bf16_f32 v5, v21, v23
	v_lshl_add_u64 v[8:9], v[6:7], 0, v[98:99]
	global_store_dwordx4 v[8:9], v[2:5], off sc1
	ds_read2_b32 v[8:9], v50 offset0:49 offset1:57
	ds_read2_b32 v[10:11], v50 offset0:16 offset1:24
	ds_read2_b32 v[12:13], v50 offset0:82 offset1:90
	ds_read2_b32 v[14:15], v50 offset0:115 offset1:123
	ds_read2_b32 v[16:17], v50 offset0:148 offset1:156
	ds_read2_b32 v[18:19], v50 offset0:181 offset1:189
	ds_read2_b32 v[20:21], v50 offset0:214 offset1:222
	ds_read2_b32 v[22:23], v50 offset0:247 offset1:255
	s_waitcnt lgkmcnt(6)
	v_cvt_pk_bf16_f32 v2, v10, v8
	v_or_b32_e32 v8, s0, v48
	v_lshlrev_b32_e32 v98, 11, v8
	v_or_b32_e32 v8, s0, v49
	s_waitcnt lgkmcnt(4)
	v_cvt_pk_bf16_f32 v3, v12, v14
	s_waitcnt lgkmcnt(2)
	v_cvt_pk_bf16_f32 v4, v16, v18
	s_waitcnt lgkmcnt(0)
	v_cvt_pk_bf16_f32 v5, v20, v22
	v_lshl_add_u64 v[24:25], v[6:7], 0, v[98:99]
	v_lshlrev_b32_e32 v98, 11, v8
	global_store_dwordx4 v[24:25], v[2:5], off sc1
	v_lshl_add_u64 v[6:7], v[6:7], 0, v[98:99]
	s_nop 0
	v_cvt_pk_bf16_f32 v2, v11, v9
	v_cvt_pk_bf16_f32 v3, v13, v15
	v_cvt_pk_bf16_f32 v4, v17, v19
	v_cvt_pk_bf16_f32 v5, v21, v23
	global_store_dwordx4 v[6:7], v[2:5], off sc1
	s_waitcnt lgkmcnt(0)
